# row-wise loops: wave sum of squares via 4 DPP adds + one bpermute + permlane32 swap instead of six dependent ds_bpermute round trips
# speedup vs baseline: 1.0051x; 1.0051x over previous
; DI int tidx() { int t = threadIdx.x; asm volatile("" : "+v"(t)); return t; }
; DI int bidx() { int b = blockIdx.x; asm volatile("" : "+s"(b)); return b; }
; DI float bf_lo(unsigned u) { return __uint_as_float(u << 16); }
; DI float bf_hi(unsigned u) { return __uint_as_float(u & 0xffff0000u); }
; DI void load_row16(const float* r, int lane, float (&v)[16]) {
; #pragma unroll
;   for (int j = 0; j < 4; ++j) { const float4 t = *(const float4*)(r + j * 256 + lane * 4); v[j * 4] = t.x; v[j * 4 + 1] = t.y; v[j * 4 + 2] = t.z; v[j * 4 + 3] = t.w; }
; }
; DI void load_row16_bf(const bf16_t* r, int lane, float (&v)[16]) {
; #pragma unroll
;   for (int j = 0; j < 4; ++j) { const uint2 t = *(const uint2*)(r + j * 256 + lane * 4); v[j * 4] = bf_lo(t.x); v[j * 4 + 1] = bf_hi(t.x); v[j * 4 + 2] = bf_lo(t.y); v[j * 4 + 3] = bf_hi(t.y); }
; }
; DI void modnorm_store(const float (&x)[16], int lane, const float* g, const float* sc, const float* sh, bf16_t* dst) {
;   float ss = 0.f;
; #pragma unroll
;   for (int i = 0; i < 16; ++i) ss += x[i] * x[i];
;   ss = wave_sum(ss);
;   const float rstd = rsqrtf(ss * (1.0f / 1024.0f) + 1e-6f);
; #pragma unroll
;   for (int j = 0; j < 4; ++j) {
;     const int c = j * 256 + lane * 4;
;     const float4 gg = *(const float4*)(g + c), s1 = *(const float4*)(sc + c), s0 = *(const float4*)(sh + c);
;     store_bf4(dst + c, x[j * 4] * rstd * gg.x * (1.f + s1.x) + s0.x, x[j * 4 + 1] * rstd * gg.y * (1.f + s1.y) + s0.y,
;               x[j * 4 + 2] * rstd * gg.z * (1.f + s1.z) + s0.z, x[j * 4 + 3] * rstd * gg.w * (1.f + s1.w) + s0.w);
;   }
; }
; DI void phase_h1(const Params& p, int hf) {
;   if (bidx() == 0 && tidx() < 64) ((float*)(p.ws + OFF_KMAX))[tidx()] = 0.f;
;   const int lane = tidx() & 63, gw = bidx() * 8 + (tidx() >> 6), nw = gridDim.x * 8;
;   const int lsh = hf == 0 ? 14 : 13;
;   const float* mod = (const float*)(p.ws + OFF_MOD);
;   bf16_t* h1 = (bf16_t*)(p.ws + OFF_H1);
;   for (int row = gw; row < HALF_TOK; row += nw) {
;     const int b = (hf == 0 ? 0 : 2) + (row >> lsh);
;     float x[16]; load_row16(p.x[hf] + (size_t)row * 1024, lane, x);
;     modnorm_store(x, lane, p.g_pre_mix, mod + b * 6144 + 1024, mod + b * 6144, h1 + (size_t)row * 1024);
;   }
; }
.LBB0_121:
	global_load_dwordx4 v[20:23], v[2:3], off offset:-2048
	global_load_dwordx4 v[24:27], v[2:3], off offset:-1024
	global_load_dwordx4 v[28:31], v[0:1], off
	global_load_dwordx4 v[32:35], v[2:3], off
	global_load_dwordx4 v[36:39], v[2:3], off offset:1024
	v_ashrrev_i32_e32 v19, s14, v12
	v_add_u32_e32 v19, s0, v19
	v_mul_lo_u32 v40, v19, s77
	v_ashrrev_i32_e32 v41, 31, v40
	v_lshl_add_u64 v[40:41], v[40:41], 2, s[56:57]
	v_lshl_add_u64 v[48:49], v[40:41], 0, s[42:43]
	v_lshl_add_u64 v[50:51], v[40:41], 0, v[152:153]
	v_lshl_add_u64 v[40:41], v[48:49], 0, v[152:153]
	global_load_dwordx4 v[40:43], v[40:41], off
	s_nop 0
	global_load_dwordx4 v[44:47], v[50:51], off
	v_lshl_add_u64 v[52:53], v[48:49], 0, v[6:7]
	v_add_u32_e32 v12, s58, v12
	v_lshl_add_u64 v[2:3], v[2:3], 0, s[90:91]
	global_load_dwordx4 v[100:103], v[0:1], off offset:1024
	global_load_dwordx4 v[104:107], v[52:53], off
	global_load_dwordx4 v[108:111], v[50:51], off offset:1024
	v_lshl_add_u64 v[112:113], v[48:49], 0, v[8:9]
	global_load_dwordx4 v[116:119], v[0:1], off offset:2048
	global_load_dwordx4 v[120:123], v[112:113], off
	global_load_dwordx4 v[124:127], v[50:51], off offset:2048
	v_lshl_add_u64 v[114:115], v[48:49], 0, v[10:11]
	global_load_dwordx4 v[128:131], v[0:1], off offset:3072
	global_load_dwordx4 v[132:135], v[114:115], off
	global_load_dwordx4 v[136:139], v[50:51], off offset:3072
	s_waitcnt vmcnt(14)
	v_pk_mul_f32 v[60:61], v[24:25], v[24:25]
	v_pk_mul_f32 v[58:59], v[26:27], v[26:27]
	v_pk_mul_f32 v[56:57], v[20:21], v[20:21]
	v_pk_mul_f32 v[54:55], v[22:23], v[22:23]
	v_add_f32_e32 v19, v56, v57
	v_add_f32_e32 v19, v19, v54
	v_add_f32_e32 v19, v19, v55
	v_add_f32_e32 v19, v19, v60
	v_add_f32_e32 v19, v19, v61
	v_add_f32_e32 v19, v19, v58
	s_waitcnt vmcnt(12)
	v_pk_mul_f32 v[64:65], v[32:33], v[32:33]
	v_add_f32_e32 v19, v19, v59
	v_add_f32_e32 v19, v19, v64
	v_pk_mul_f32 v[62:63], v[34:35], v[34:35]
	v_add_f32_e32 v19, v19, v65
	v_add_f32_e32 v19, v19, v62
	s_waitcnt vmcnt(11)
	v_pk_mul_f32 v[68:69], v[36:37], v[36:37]
	v_add_f32_e32 v19, v19, v63
	v_add_f32_e32 v19, v19, v68
	v_pk_mul_f32 v[66:67], v[38:39], v[38:39]
	v_add_f32_e32 v19, v19, v69
	v_add_f32_e32 v19, v19, v66
	v_add_f32_e32 v19, v19, v67
	s_nop 1
	v_add_f32_dpp v19, v19, v19 quad_perm:[1,0,3,2] row_mask:0xf bank_mask:0xf
	s_nop 1
	v_add_f32_dpp v19, v19, v19 quad_perm:[2,3,0,1] row_mask:0xf bank_mask:0xf
	s_nop 1
	v_add_f32_dpp v19, v19, v19 row_ror:4 row_mask:0xf bank_mask:0xf
	s_nop 1
	v_add_f32_dpp v19, v19, v19 row_ror:8 row_mask:0xf bank_mask:0xf
	ds_bpermute_b32 v54, v14, v19
	s_waitcnt vmcnt(10)
	v_pk_add_f32 v[40:41], v[40:41], 1.0 op_sel_hi:[1, 0]
	v_pk_add_f32 v[42:43], v[42:43], 1.0 op_sel_hi:[1, 0]
	s_waitcnt lgkmcnt(0)
	v_add_f32_e32 v19, v19, v54
	v_mov_b32_e32 v54, v19
	s_nop 1
	v_permlane32_swap_b32_e32 v19, v54
	v_add_f32_e32 v19, v19, v54
	v_fmamk_f32 v19, v19, 0x3a800000, v163
	v_mul_f32_e32 v54, 0x4b800000, v19
	v_cmp_gt_f32_e32 vcc, s21, v19
	s_nop 1
	v_cndmask_b32_e32 v19, v19, v54, vcc
	v_rsq_f32_e32 v19, v19
	s_nop 0
	v_mul_f32_e32 v54, 0x45800000, v19
	v_cndmask_b32_e32 v54, v19, v54, vcc
	v_pk_mul_f32 v[20:21], v[20:21], v[54:55] op_sel_hi:[1, 0]
	v_pk_mul_f32 v[22:23], v[22:23], v[54:55] op_sel_hi:[1, 0]
	v_pk_mul_f32 v[20:21], v[28:29], v[20:21]
	v_pk_mul_f32 v[22:23], v[30:31], v[22:23]
	s_waitcnt vmcnt(9)
	v_pk_fma_f32 v[20:21], v[40:41], v[20:21], v[44:45]
	v_pk_fma_f32 v[22:23], v[42:43], v[22:23], v[46:47]
	v_cvt_pk_bf16_f32 v20, v20, v21
	v_cvt_pk_bf16_f32 v21, v22, v23
	global_store_dwordx2 v[4:5], v[20:21], off offset:-1024
	s_nop 0
	v_pk_mul_f32 v[24:25], v[24:25], v[54:55] op_sel_hi:[1, 0]
	v_pk_mul_f32 v[26:27], v[26:27], v[54:55] op_sel_hi:[1, 0]
	v_pk_mul_f32 v[32:33], v[32:33], v[54:55] op_sel_hi:[1, 0]
	v_pk_mul_f32 v[34:35], v[34:35], v[54:55] op_sel_hi:[1, 0]
	v_cmp_lt_i32_e32 vcc, s96, v12
	s_or_b64 s[8:9], vcc, s[8:9]
	s_waitcnt vmcnt(9)
	v_pk_mul_f32 v[20:21], v[24:25], v[100:101]
	s_waitcnt vmcnt(8)
	v_pk_add_f32 v[24:25], v[104:105], 1.0 op_sel_hi:[1, 0]
	v_pk_mul_f32 v[22:23], v[26:27], v[102:103]
	v_pk_add_f32 v[26:27], v[106:107], 1.0 op_sel_hi:[1, 0]
	s_waitcnt vmcnt(7)
	v_pk_fma_f32 v[20:21], v[20:21], v[24:25], v[108:109]
	v_pk_fma_f32 v[22:23], v[22:23], v[26:27], v[110:111]
	v_cvt_pk_bf16_f32 v20, v20, v21
	v_cvt_pk_bf16_f32 v21, v22, v23
	global_store_dwordx2 v[4:5], v[20:21], off offset:-512
	s_nop 0
	s_waitcnt vmcnt(7)
	v_pk_mul_f32 v[20:21], v[32:33], v[116:117]
	s_waitcnt vmcnt(6)
	v_pk_add_f32 v[24:25], v[120:121], 1.0 op_sel_hi:[1, 0]
	v_pk_mul_f32 v[22:23], v[34:35], v[118:119]
	v_pk_add_f32 v[26:27], v[122:123], 1.0 op_sel_hi:[1, 0]
	s_waitcnt vmcnt(5)
	v_pk_fma_f32 v[20:21], v[20:21], v[24:25], v[124:125]
	v_pk_fma_f32 v[22:23], v[22:23], v[26:27], v[126:127]
	v_cvt_pk_bf16_f32 v20, v20, v21
	v_cvt_pk_bf16_f32 v21, v22, v23
	global_store_dwordx2 v[4:5], v[20:21], off
	s_nop 0
	v_pk_mul_f32 v[32:33], v[36:37], v[54:55] op_sel_hi:[1, 0]
	v_pk_mul_f32 v[34:35], v[38:39], v[54:55] op_sel_hi:[1, 0]
	s_waitcnt vmcnt(5)
	v_pk_mul_f32 v[20:21], v[32:33], v[128:129]
	s_waitcnt vmcnt(4)
	v_pk_add_f32 v[24:25], v[132:133], 1.0 op_sel_hi:[1, 0]
	v_pk_mul_f32 v[22:23], v[34:35], v[130:131]
	v_pk_add_f32 v[26:27], v[134:135], 1.0 op_sel_hi:[1, 0]
	s_waitcnt vmcnt(3)
	v_pk_fma_f32 v[20:21], v[20:21], v[24:25], v[136:137]
	v_pk_fma_f32 v[22:23], v[22:23], v[26:27], v[138:139]
	v_cvt_pk_bf16_f32 v20, v20, v21
	v_cvt_pk_bf16_f32 v21, v22, v23
	global_store_dwordx2 v[4:5], v[20:21], off offset:512
	v_lshl_add_u64 v[4:5], v[4:5], 0, s[84:85]
	s_andn2_b64 exec, exec, s[8:9]
	s_cbranch_execnz .LBB0_121

; DI int tidx() { int t = threadIdx.x; asm volatile("" : "+v"(t)); return t; }
; DI int bidx() { int b = blockIdx.x; asm volatile("" : "+s"(b)); return b; }
; DI void phase_x1(const Params& p, int hf) {
;   const int lane = tidx() & 63, gw = bidx() * 8 + (tidx() >> 6), nw = gridDim.x * 8;
;   const int lsh = hf == 0 ? 14 : 13;
;   const float* mod = (const float*)(p.ws + OFF_MOD);
;   const bf16_t* mix = (const bf16_t*)(p.ws + OFF_V);
;   bf16_t* h2 = (bf16_t*)(p.ws + OFF_H1);
;   float* outp = p.out + (size_t)hf * HALF_TOK * 1024;
;   for (int row = gw; row < HALF_TOK; row += nw) {
;     const int b = (hf == 0 ? 0 : 2) + (row >> lsh);
;     const float* mb = mod + b * 6144;
;     float x[16], m[16];
;     load_row16(p.x[hf] + (size_t)row * 1024, lane, x);
;     load_row16_bf(mix + (size_t)row * 1024, lane, m);
;     float ss = 0.f;
; #pragma unroll
;     for (int i = 0; i < 16; ++i) ss += m[i] * m[i];
;     ss = wave_sum(ss);
;     const float rstd = rsqrtf(ss * (1.0f / 1024.0f) + 1e-6f);
; #pragma unroll
;     for (int j = 0; j < 4; ++j) {
;       const int c = j * 256 + lane * 4;
;       const float4 gg = *(const float4*)(p.g_post_mix + c), gt = *(const float4*)(mb + 2048 + c);
;       x[j * 4] += gt.x * m[j * 4] * rstd * gg.x; x[j * 4 + 1] += gt.y * m[j * 4 + 1] * rstd * gg.y;
;       x[j * 4 + 2] += gt.z * m[j * 4 + 2] * rstd * gg.z; x[j * 4 + 3] += gt.w * m[j * 4 + 3] * rstd * gg.w;
;       *(float4*)(outp + (size_t)row * 1024 + c) = make_float4(x[j * 4], x[j * 4 + 1], x[j * 4 + 2], x[j * 4 + 3]);
;     }
;     modnorm_store(x, lane, p.g_pre_ffn, mb + 4096, mb + 3072, h2 + (size_t)row * 1024);
.LBB0_325:
	global_load_dwordx2 v[2:3], v[16:17], off
	v_ashrrev_i32_e32 v0, s14, v40
	v_add_u32_e32 v0, s0, v0
	v_mul_lo_u32 v0, v0, s77
	v_ashrrev_i32_e32 v1, 31, v0
	v_lshl_add_u64 v[30:31], v[0:1], 2, s[56:57]
	v_lshl_add_u64 v[62:63], v[30:31], 0, s[78:79]
	v_lshl_add_u64 v[60:61], v[20:21], 0, v[18:19]
	v_lshl_add_u64 v[0:1], v[62:63], 0, v[152:153]
	global_load_dwordx4 v[48:51], v[60:61], off
	v_lshl_add_u64 v[36:37], v[22:23], 0, v[18:19]
	v_mov_b32_e32 v25, v153
	v_mov_b32_e32 v27, v153
	v_mov_b32_e32 v29, v153
	v_lshl_add_u64 v[72:73], v[62:63], 0, v[24:25]
	v_lshl_add_u64 v[78:79], v[62:63], 0, v[26:27]
	s_mov_b64 s[22:23], 0x4000
	s_brev_b32 s1, 47
	v_add_u32_e32 v40, s58, v40
	v_lshl_add_u64 v[20:21], v[20:21], 0, s[90:91]
	v_lshl_add_u64 v[22:23], v[22:23], 0, s[90:91]
	global_load_dwordx2 v[100:101], v[16:17], off offset:512
	global_load_dwordx2 v[102:103], v[16:17], off offset:1024
	global_load_dwordx2 v[104:105], v[16:17], off offset:1536
	global_load_dwordx4 v[108:111], v[12:13], off
	global_load_dwordx4 v[112:115], v[0:1], off
	global_load_dwordx4 v[116:119], v[60:61], off offset:1024
	global_load_dwordx4 v[120:123], v[60:61], off offset:2048
	v_lshl_add_u64 v[106:107], v[62:63], 0, v[28:29]
	global_load_dwordx4 v[124:127], v[60:61], off offset:3072
	global_load_dwordx4 v[128:131], v[12:13], off offset:1024
	global_load_dwordx4 v[132:135], v[72:73], off
	global_load_dwordx4 v[136:139], v[12:13], off offset:2048
	global_load_dwordx4 v[140:143], v[78:79], off
	global_load_dwordx4 v[144:147], v[12:13], off offset:3072
	global_load_dwordx4 v[148:151], v[106:107], off
	v_lshl_add_u64 v[184:185], v[30:31], 0, s[22:23]
	v_lshl_add_u64 v[186:187], v[184:185], 0, v[152:153]
	global_load_dwordx4 v[188:191], v[14:15], off
	global_load_dwordx4 v[192:195], v[186:187], off
	v_lshl_add_u64 v[196:197], v[184:185], 0, v[24:25]
	global_load_dwordx4 v[200:203], v[14:15], off offset:1024
	global_load_dwordx4 v[204:207], v[196:197], off
	v_lshl_add_u64 v[198:199], v[184:185], 0, v[26:27]
	global_load_dwordx4 v[208:211], v[14:15], off offset:2048
	global_load_dwordx4 v[212:215], v[198:199], off
	v_lshl_add_u64 v[216:217], v[184:185], 0, v[28:29]
	global_load_dwordx4 v[220:223], v[14:15], off offset:3072
	global_load_dwordx4 v[224:227], v[216:217], off
	s_waitcnt vmcnt(23)
	v_lshlrev_b32_e32 v38, 16, v2
	v_and_b32_e32 v39, 0xffff0000, v2
	v_lshlrev_b32_e32 v56, 16, v3
	v_and_b32_e32 v57, 0xffff0000, v3
	v_pk_mul_f32 v[64:65], v[38:39], v[38:39]
	v_pk_mul_f32 v[68:69], v[56:57], v[56:57]
	v_add_f32_e32 v47, v64, v65
	v_add_f32_e32 v47, v47, v68
	v_add_f32_e32 v47, v69, v47
	s_waitcnt vmcnt(21)
	v_lshlrev_b32_e32 v8, 16, v100
	v_and_b32_e32 v9, 0xffff0000, v100
	v_lshlrev_b32_e32 v10, 16, v101
	v_and_b32_e32 v11, 0xffff0000, v101
	v_pk_mul_f32 v[74:75], v[8:9], v[8:9]
	v_pk_mul_f32 v[76:77], v[10:11], v[10:11]
	v_add_f32_e32 v47, v74, v47
	v_add_f32_e32 v47, v75, v47
	v_add_f32_e32 v47, v76, v47
	v_add_f32_e32 v47, v77, v47
	s_waitcnt vmcnt(20)
	v_lshlrev_b32_e32 v4, 16, v102
	v_and_b32_e32 v5, 0xffff0000, v102
	v_lshlrev_b32_e32 v6, 16, v103
	v_and_b32_e32 v7, 0xffff0000, v103
	v_pk_mul_f32 v[80:81], v[4:5], v[4:5]
	v_pk_mul_f32 v[82:83], v[6:7], v[6:7]
	v_add_f32_e32 v47, v80, v47
	v_add_f32_e32 v47, v81, v47
	v_add_f32_e32 v47, v82, v47
	v_add_f32_e32 v47, v83, v47
	s_waitcnt vmcnt(19)
	v_lshlrev_b32_e32 v34, 16, v104
	v_and_b32_e32 v35, 0xffff0000, v104
	v_lshlrev_b32_e32 v32, 16, v105
	v_and_b32_e32 v33, 0xffff0000, v105
	s_nop 0
	v_pk_mul_f32 v[84:85], v[34:35], v[34:35]
	v_pk_mul_f32 v[86:87], v[32:33], v[32:33]
	v_add_f32_e32 v47, v84, v47
	v_add_f32_e32 v47, v85, v47
	v_add_f32_e32 v47, v86, v47
	v_add_f32_e32 v47, v87, v47
	s_nop 1
	v_add_f32_dpp v47, v47, v47 quad_perm:[1,0,3,2] row_mask:0xf bank_mask:0xf
	s_nop 1
	v_add_f32_dpp v47, v47, v47 quad_perm:[2,3,0,1] row_mask:0xf bank_mask:0xf
	s_nop 1
	v_add_f32_dpp v47, v47, v47 row_ror:4 row_mask:0xf bank_mask:0xf
	s_nop 1
	v_add_f32_dpp v47, v47, v47 row_ror:8 row_mask:0xf bank_mask:0xf
	ds_bpermute_b32 v64, v42, v47
	s_waitcnt lgkmcnt(0)
	v_add_f32_e32 v47, v47, v64
	v_mov_b32_e32 v64, v47
	s_nop 1
	v_permlane32_swap_b32_e32 v47, v64
	v_add_f32_e32 v47, v47, v64
	v_fmamk_f32 v47, v47, 0x3a800000, v163
	v_cmp_gt_f32_e32 vcc, s21, v47
	v_mul_f32_e32 v64, 0x4b800000, v47
	s_waitcnt vmcnt(17)
	v_pk_mul_f32 v[66:67], v[112:113], v[38:39]
	v_cndmask_b32_e32 v47, v47, v64, vcc
	v_rsq_f32_e32 v47, v47
	v_pk_mul_f32 v[70:71], v[114:115], v[56:57]
	v_mul_f32_e32 v64, 0x45800000, v47
	v_cndmask_b32_e32 v68, v47, v64, vcc
	v_pk_mul_f32 v[64:65], v[66:67], v[68:69] op_sel_hi:[1, 0]
	v_pk_fma_f32 v[48:49], v[108:109], v[64:65], v[48:49]
	v_pk_mul_f32 v[52:53], v[70:71], v[68:69] op_sel_hi:[1, 0]
	v_pk_fma_f32 v[50:51], v[110:111], v[52:53], v[50:51]
	global_store_dwordx4 v[36:37], v[48:51], off
	s_nop 1
	s_waitcnt vmcnt(13)
	v_pk_mul_f32 v[8:9], v[132:133], v[8:9]
	v_pk_mul_f32 v[10:11], v[134:135], v[10:11]
	v_pk_mul_f32 v[8:9], v[68:69], v[8:9] op_sel_hi:[0, 1]
	v_pk_mul_f32 v[10:11], v[68:69], v[10:11] op_sel_hi:[0, 1]
	v_pk_fma_f32 v[8:9], v[128:129], v[8:9], v[116:117]
	v_pk_fma_f32 v[10:11], v[130:131], v[10:11], v[118:119]
	global_store_dwordx4 v[36:37], v[8:11], off offset:1024
	s_nop 1
	s_waitcnt vmcnt(12)
; DI void modnorm_store(const float (&x)[16], int lane, const float* g, const float* sc, const float* sh, bf16_t* dst) {
;   float ss = 0.f;
; #pragma unroll
;   for (int i = 0; i < 16; ++i) ss += x[i] * x[i];
;   ss = wave_sum(ss);
;   const float rstd = rsqrtf(ss * (1.0f / 1024.0f) + 1e-6f);
; #pragma unroll
;   for (int j = 0; j < 4; ++j) {
;     const int c = j * 256 + lane * 4;
;     const float4 gg = *(const float4*)(g + c), s1 = *(const float4*)(sc + c), s0 = *(const float4*)(sh + c);
;     store_bf4(dst + c, x[j * 4] * rstd * gg.x * (1.f + s1.x) + s0.x, x[j * 4 + 1] * rstd * gg.y * (1.f + s1.y) + s0.y,
;               x[j * 4 + 2] * rstd * gg.z * (1.f + s1.z) + s0.z, x[j * 4 + 3] * rstd * gg.w * (1.f + s1.w) + s0.w);
;   }
; }
; DI void phase_x1(const Params& p, int hf) {
;     ...
; #pragma unroll
;     for (int j = 0; j < 4; ++j) {
;       const int c = j * 256 + lane * 4;
;       const float4 gg = *(const float4*)(p.g_post_mix + c), gt = *(const float4*)(mb + 2048 + c);
;       x[j * 4] += gt.x * m[j * 4] * rstd * gg.x; x[j * 4 + 1] += gt.y * m[j * 4 + 1] * rstd * gg.y;
;       x[j * 4 + 2] += gt.z * m[j * 4 + 2] * rstd * gg.z; x[j * 4 + 3] += gt.w * m[j * 4 + 3] * rstd * gg.w;
;       *(float4*)(outp + (size_t)row * 1024 + c) = make_float4(x[j * 4], x[j * 4 + 1], x[j * 4 + 2], x[j * 4 + 3]);
;     }
;     modnorm_store(x, lane, p.g_pre_ffn, mb + 4096, mb + 3072, h2 + (size_t)row * 1024);
	v_pk_mul_f32 v[4:5], v[140:141], v[4:5]
	s_nop 0
	v_pk_mul_f32 v[4:5], v[68:69], v[4:5] op_sel_hi:[0, 1]
	v_pk_fma_f32 v[4:5], v[136:137], v[4:5], v[120:121]
	v_pk_mul_f32 v[0:1], v[142:143], v[6:7]
	s_nop 0
	v_pk_mul_f32 v[0:1], v[68:69], v[0:1] op_sel_hi:[0, 1]
	v_pk_fma_f32 v[6:7], v[138:139], v[0:1], v[122:123]
	global_store_dwordx4 v[36:37], v[4:7], off offset:2048
	s_nop 1
	v_pk_mul_f32 v[38:39], v[8:9], v[8:9]
	v_pk_mul_f32 v[56:57], v[6:7], v[6:7]
	s_waitcnt vmcnt(11)
	v_pk_mul_f32 v[32:33], v[150:151], v[32:33]
	v_pk_mul_f32 v[34:35], v[148:149], v[34:35]
	v_pk_mul_f32 v[32:33], v[68:69], v[32:33] op_sel_hi:[0, 1]
	v_pk_mul_f32 v[34:35], v[68:69], v[34:35] op_sel_hi:[0, 1]
	v_pk_fma_f32 v[2:3], v[146:147], v[32:33], v[126:127]
	s_mov_b64 s[22:23], 0x3000
	v_pk_fma_f32 v[0:1], v[144:145], v[34:35], v[124:125]
	v_lshl_add_u64 v[34:35], v[30:31], 0, s[22:23]
	v_pk_mul_f32 v[30:31], v[48:49], v[48:49]
	global_store_dwordx4 v[36:37], v[0:3], off offset:3072
	s_nop 1
	v_pk_mul_f32 v[36:37], v[50:51], v[50:51]
	v_add_f32_e32 v30, v30, v31
	v_add_f32_e32 v30, v36, v30
	v_add_f32_e32 v30, v37, v30
	v_add_f32_e32 v30, v38, v30
	v_pk_mul_f32 v[52:53], v[10:11], v[10:11]
	v_add_f32_e32 v30, v39, v30
	v_add_f32_e32 v30, v52, v30
	v_pk_mul_f32 v[54:55], v[4:5], v[4:5]
	v_add_f32_e32 v30, v53, v30
	v_add_f32_e32 v30, v30, v54
	v_add_f32_e32 v30, v55, v30
	v_add_f32_e32 v30, v56, v30
	v_pk_mul_f32 v[58:59], v[0:1], v[0:1]
	v_add_f32_e32 v30, v57, v30
	v_add_f32_e32 v30, v30, v58
	v_lshl_add_u64 v[56:57], v[34:35], 0, v[152:153]
	v_add_f32_e32 v30, v59, v30
	s_nop 0
	s_nop 0
	global_load_dwordx4 v[56:59], v[56:57], off
	v_pk_mul_f32 v[60:61], v[2:3], v[2:3]
	s_nop 0
	v_add_f32_e32 v30, v60, v30
	v_add_f32_e32 v30, v61, v30
	s_nop 1
	v_add_f32_dpp v30, v30, v30 quad_perm:[1,0,3,2] row_mask:0xf bank_mask:0xf
	s_nop 1
	v_add_f32_dpp v30, v30, v30 quad_perm:[2,3,0,1] row_mask:0xf bank_mask:0xf
	s_nop 1
	v_add_f32_dpp v30, v30, v30 row_ror:4 row_mask:0xf bank_mask:0xf
	s_nop 1
	v_add_f32_dpp v30, v30, v30 row_ror:8 row_mask:0xf bank_mask:0xf
	ds_bpermute_b32 v31, v42, v30
	s_waitcnt lgkmcnt(0)
	v_add_f32_e32 v30, v30, v31
	v_mov_b32_e32 v31, v30
	s_nop 1
	v_permlane32_swap_b32_e32 v30, v31
	v_add_f32_e32 v30, v30, v31
	v_fmamk_f32 v30, v30, 0x3a800000, v163
	v_cmp_gt_f32_e32 vcc, s21, v30
	v_mul_f32_e32 v31, 0x4b800000, v30
	s_nop 0
	v_cndmask_b32_e32 v30, v30, v31, vcc
	v_rsq_f32_e32 v30, v30
	s_nop 0
	v_mul_f32_e32 v31, 0x45800000, v30
	v_cndmask_b32_e32 v30, v30, v31, vcc
	v_pk_mul_f32 v[48:49], v[48:49], v[30:31] op_sel_hi:[1, 0]
	v_pk_mul_f32 v[8:9], v[8:9], v[30:31] op_sel_hi:[1, 0]
	v_pk_mul_f32 v[10:11], v[10:11], v[30:31] op_sel_hi:[1, 0]
	v_pk_mul_f32 v[4:5], v[4:5], v[30:31] op_sel_hi:[1, 0]
	v_pk_mul_f32 v[6:7], v[6:7], v[30:31] op_sel_hi:[1, 0]
	v_pk_mul_f32 v[0:1], v[0:1], v[30:31] op_sel_hi:[1, 0]
	v_pk_mul_f32 v[2:3], v[2:3], v[30:31] op_sel_hi:[1, 0]
	s_waitcnt vmcnt(12)
	v_pk_mul_f32 v[36:37], v[188:189], v[48:49]
	s_waitcnt vmcnt(11)
	v_pk_add_f32 v[48:49], v[192:193], 1.0 op_sel_hi:[1, 0]
	v_lshl_add_u64 v[52:53], v[34:35], 0, v[24:25]
	s_waitcnt vmcnt(0)
	v_pk_fma_f32 v[36:37], v[48:49], v[36:37], v[56:57]
	v_pk_mul_f32 v[48:49], v[50:51], v[30:31] op_sel_hi:[1, 0]
	v_cvt_pk_bf16_f32 v36, v36, v37
	v_pk_mul_f32 v[38:39], v[190:191], v[48:49]
	v_pk_add_f32 v[48:49], v[194:195], 1.0 op_sel_hi:[1, 0]
	s_nop 0
	v_pk_fma_f32 v[38:39], v[48:49], v[38:39], v[58:59]
	v_cvt_pk_bf16_f32 v37, v38, v39
	v_add_co_u32_e32 v38, vcc, s1, v16
	s_mov_b32 s1, 0xf4001000
	s_nop 0
	v_addc_co_u32_e32 v39, vcc, -1, v17, vcc
	global_store_dwordx2 v[38:39], v[36:37], off
	s_nop 0
	s_nop 0
	global_load_dwordx4 v[52:55], v[52:53], off
	v_pk_mul_f32 v[8:9], v[8:9], v[200:201]
	v_pk_add_f32 v[36:37], v[204:205], 1.0 op_sel_hi:[1, 0]
	v_pk_mul_f32 v[10:11], v[10:11], v[202:203]
	s_waitcnt vmcnt(0)
	v_pk_fma_f32 v[8:9], v[8:9], v[36:37], v[52:53]
	v_pk_add_f32 v[36:37], v[206:207], 1.0 op_sel_hi:[1, 0]
	v_add_co_u32_e32 v52, vcc, s1, v16
	v_pk_fma_f32 v[10:11], v[10:11], v[36:37], v[54:55]
	v_cvt_pk_bf16_f32 v8, v8, v9
	v_cvt_pk_bf16_f32 v9, v10, v11
	v_addc_co_u32_e32 v53, vcc, -1, v17, vcc
	global_store_dwordx2 v[52:53], v[8:9], off offset:-3584
	v_lshl_add_u64 v[48:49], v[34:35], 0, v[26:27]
	s_nop 0
	s_nop 0
	global_load_dwordx4 v[48:51], v[48:49], off
	v_cmp_lt_i32_e32 vcc, s96, v40
	v_lshl_add_u64 v[16:17], v[16:17], 0, s[84:85]
	s_or_b64 s[24:25], vcc, s[24:25]
	v_pk_mul_f32 v[4:5], v[4:5], v[208:209]
	v_pk_add_f32 v[8:9], v[212:213], 1.0 op_sel_hi:[1, 0]
	v_pk_mul_f32 v[6:7], v[6:7], v[210:211]
	s_waitcnt vmcnt(0)
	v_pk_fma_f32 v[4:5], v[4:5], v[8:9], v[48:49]
	v_pk_add_f32 v[8:9], v[214:215], 1.0 op_sel_hi:[1, 0]
	v_cvt_pk_bf16_f32 v4, v4, v5
	v_pk_fma_f32 v[6:7], v[6:7], v[8:9], v[50:51]
	v_cvt_pk_bf16_f32 v5, v6, v7
	global_store_dwordx2 v[52:53], v[4:5], off offset:-3072
	v_lshl_add_u64 v[32:33], v[34:35], 0, v[28:29]
	s_nop 0
	s_nop 0
	global_load_dwordx4 v[32:35], v[32:33], off
	v_pk_mul_f32 v[0:1], v[0:1], v[220:221]
	v_pk_add_f32 v[4:5], v[224:225], 1.0 op_sel_hi:[1, 0]
	v_pk_mul_f32 v[2:3], v[2:3], v[222:223]
	s_waitcnt vmcnt(0)
	v_pk_fma_f32 v[0:1], v[0:1], v[4:5], v[32:33]
	v_pk_add_f32 v[4:5], v[226:227], 1.0 op_sel_hi:[1, 0]
	v_cvt_pk_bf16_f32 v0, v0, v1
	v_pk_fma_f32 v[2:3], v[2:3], v[4:5], v[34:35]
	s_nop 0
	v_cvt_pk_bf16_f32 v1, v2, v3
	global_store_dwordx2 v[52:53], v[0:1], off offset:-2560
	s_andn2_b64 exec, exec, s[24:25]
	s_cbranch_execnz .LBB0_325

; DI int tidx() { int t = threadIdx.x; asm volatile("" : "+v"(t)); return t; }
; DI int bidx() { int b = blockIdx.x; asm volatile("" : "+s"(b)); return b; }
; DI void phase_final(const Params& p, int hf) {
;   const int lane = tidx() & 63, gw = bidx() * 8 + (tidx() >> 6), nw = gridDim.x * 8;
;   const int lsh = hf == 0 ? 14 : 13;
;   const float* mod = (const float*)(p.ws + OFF_MOD);
;   const bf16_t* fb = (const bf16_t*)(p.ws + OFF_H1);
;   float* outp = p.out + (size_t)hf * HALF_TOK * 1024;
;   for (int row = gw; row < HALF_TOK; row += nw) {
;     const int b = (hf == 0 ? 0 : 2) + (row >> lsh);
;     const float* mb = mod + b * 6144;
;     float x[16], m[16];
;     load_row16(outp + (size_t)row * 1024, lane, x);
;     load_row16_bf(fb + (size_t)row * 1024, lane, m);
;     float ss = 0.f;
; #pragma unroll
;     for (int i = 0; i < 16; ++i) ss += m[i] * m[i];
;     ss = wave_sum(ss);
;     const float rstd = rsqrtf(ss * (1.0f / 1024.0f) + 1e-6f);
; #pragma unroll
;     for (int j = 0; j < 4; ++j) {
;       const int c = j * 256 + lane * 4;
;       const float4 gg = *(const float4*)(p.g_post_ffn + c), gt = *(const float4*)(mb + 5120 + c);
;       *(float4*)(outp + (size_t)row * 1024 + c) =
;           make_float4(x[j * 4] + gt.x * m[j * 4] * rstd * gg.x, x[j * 4 + 1] + gt.y * m[j * 4 + 1] * rstd * gg.y,
;                       x[j * 4 + 2] + gt.z * m[j * 4 + 2] * rstd * gg.z, x[j * 4 + 3] + gt.w * m[j * 4 + 3] * rstd * gg.w);
;     }
;   }
; }
.LBB0_376:
	global_load_dwordx2 v[36:37], v[2:3], off offset:-1024
	global_load_dwordx2 v[38:39], v[2:3], off offset:-512
	global_load_dwordx2 v[40:41], v[2:3], off
	global_load_dwordx2 v[42:43], v[2:3], off offset:512
	v_ashrrev_i32_e32 v9, s1, v12
	v_add_u32_e32 v9, s0, v9
	v_mul_lo_u32 v32, v9, s77
	v_ashrrev_i32_e32 v33, 31, v32
	v_lshl_add_u64 v[32:33], v[32:33], 2, s[10:11]
	s_mov_b64 s[22:23], 0x4285000
	v_lshl_add_u64 v[44:45], v[32:33], 0, s[22:23]
	v_lshl_add_u64 v[32:33], v[44:45], 0, v[152:153]
	global_load_dwordx4 v[20:23], v[0:1], off
	global_load_dwordx4 v[24:27], v[4:5], off offset:-2048
	global_load_dwordx4 v[28:31], v[4:5], off offset:-1024
	v_mov_b32_e32 v7, v153
	global_load_dwordx4 v[32:35], v[32:33], off
	v_lshl_add_u64 v[46:47], v[44:45], 0, v[6:7]
	v_mov_b32_e32 v11, v153
	v_add_u32_e32 v12, s58, v12
	v_lshl_add_u64 v[2:3], v[2:3], 0, s[84:85]
	global_load_dwordx4 v[100:103], v[46:47], off
	global_load_dwordx4 v[104:107], v[0:1], off offset:1024
	v_mov_b32_e32 v108, v153
	v_mov_b32_e32 v110, v8
	v_mov_b32_e32 v111, v108
	v_lshl_add_u64 v[112:113], v[44:45], 0, v[110:111]
	global_load_dwordx4 v[116:119], v[4:5], off
	global_load_dwordx4 v[120:123], v[112:113], off
	global_load_dwordx4 v[124:127], v[0:1], off offset:2048
	v_lshl_add_u64 v[114:115], v[44:45], 0, v[10:11]
	global_load_dwordx4 v[128:131], v[4:5], off offset:1024
	global_load_dwordx4 v[132:135], v[114:115], off
	global_load_dwordx4 v[136:139], v[0:1], off offset:3072
	s_waitcnt vmcnt(15)
	v_lshlrev_b32_e32 v48, 16, v36
	v_and_b32_e32 v49, 0xffff0000, v36
	v_lshlrev_b32_e32 v36, 16, v37
	v_and_b32_e32 v37, 0xffff0000, v37
	v_pk_mul_f32 v[56:57], v[48:49], v[48:49]
	v_pk_mul_f32 v[58:59], v[36:37], v[36:37]
	v_add_f32_e32 v7, v56, v57
	s_waitcnt vmcnt(14)
	v_lshlrev_b32_e32 v50, 16, v38
	v_and_b32_e32 v51, 0xffff0000, v38
	v_add_f32_e32 v7, v7, v58
	v_pk_mul_f32 v[60:61], v[50:51], v[50:51]
	v_add_f32_e32 v7, v59, v7
	v_lshlrev_b32_e32 v38, 16, v39
	v_and_b32_e32 v39, 0xffff0000, v39
	v_add_f32_e32 v7, v60, v7
	v_pk_mul_f32 v[62:63], v[38:39], v[38:39]
	v_add_f32_e32 v7, v61, v7
	s_waitcnt vmcnt(13)
	v_lshlrev_b32_e32 v52, 16, v40
	v_and_b32_e32 v53, 0xffff0000, v40
	v_add_f32_e32 v7, v62, v7
	v_pk_mul_f32 v[64:65], v[52:53], v[52:53]
	v_add_f32_e32 v7, v63, v7
	v_lshlrev_b32_e32 v40, 16, v41
	v_and_b32_e32 v41, 0xffff0000, v41
	v_add_f32_e32 v7, v64, v7
	v_pk_mul_f32 v[66:67], v[40:41], v[40:41]
	v_add_f32_e32 v7, v65, v7
	s_waitcnt vmcnt(12)
	v_lshlrev_b32_e32 v54, 16, v42
	v_and_b32_e32 v55, 0xffff0000, v42
	v_add_f32_e32 v7, v66, v7
	v_pk_mul_f32 v[68:69], v[54:55], v[54:55]
	v_add_f32_e32 v7, v67, v7
	v_lshlrev_b32_e32 v42, 16, v43
	v_and_b32_e32 v43, 0xffff0000, v43
	v_add_f32_e32 v7, v68, v7
	v_pk_mul_f32 v[70:71], v[42:43], v[42:43]
	v_add_f32_e32 v7, v69, v7
	v_add_f32_e32 v7, v70, v7
	v_add_f32_e32 v7, v71, v7
	s_nop 1
	v_add_f32_dpp v7, v7, v7 quad_perm:[1,0,3,2] row_mask:0xf bank_mask:0xf
	s_nop 1
	v_add_f32_dpp v7, v7, v7 quad_perm:[2,3,0,1] row_mask:0xf bank_mask:0xf
	s_nop 1
	v_add_f32_dpp v7, v7, v7 row_ror:4 row_mask:0xf bank_mask:0xf
	s_nop 1
	v_add_f32_dpp v7, v7, v7 row_ror:8 row_mask:0xf bank_mask:0xf
	ds_bpermute_b32 v9, v14, v7
	s_waitcnt vmcnt(8)
	v_pk_mul_f32 v[32:33], v[32:33], v[48:49]
	v_pk_mul_f32 v[34:35], v[34:35], v[36:37]
	s_waitcnt lgkmcnt(0)
	v_add_f32_e32 v7, v7, v9
	v_mov_b32_e32 v9, v7
	s_nop 1
	v_permlane32_swap_b32_e32 v7, v9
	v_add_f32_e32 v7, v7, v9
	v_fmamk_f32 v7, v7, 0x3a800000, v163
	v_mul_f32_e32 v9, 0x4b800000, v7
	v_cmp_gt_f32_e32 vcc, s21, v7
	s_nop 1
	v_cndmask_b32_e32 v7, v7, v9, vcc
	v_rsq_f32_e32 v7, v7
	s_nop 0
	v_mul_f32_e32 v9, 0x45800000, v7
	v_cndmask_b32_e32 v36, v7, v9, vcc
	v_pk_mul_f32 v[32:33], v[32:33], v[36:37] op_sel_hi:[1, 0]
	v_pk_mul_f32 v[34:35], v[34:35], v[36:37] op_sel_hi:[1, 0]
	v_pk_fma_f32 v[20:21], v[20:21], v[32:33], v[24:25]
	v_pk_fma_f32 v[22:23], v[22:23], v[34:35], v[26:27]
	global_store_dwordx4 v[4:5], v[20:23], off offset:-2048
	s_nop 1
	s_nop 0
	v_cmp_lt_i32_e32 vcc, s96, v12
	s_or_b64 s[4:5], vcc, s[4:5]
	s_waitcnt vmcnt(8)
	v_pk_mul_f32 v[20:21], v[100:101], v[50:51]
	v_pk_mul_f32 v[22:23], v[102:103], v[38:39]
	v_pk_mul_f32 v[20:21], v[36:37], v[20:21] op_sel_hi:[0, 1]
	v_pk_mul_f32 v[22:23], v[36:37], v[22:23] op_sel_hi:[0, 1]
	s_waitcnt vmcnt(7)
	v_pk_fma_f32 v[20:21], v[104:105], v[20:21], v[28:29]
	v_pk_fma_f32 v[22:23], v[106:107], v[22:23], v[30:31]
	global_store_dwordx4 v[4:5], v[20:23], off offset:-1024
	s_nop 1
	s_nop 0
	s_waitcnt vmcnt(6)
	v_pk_mul_f32 v[20:21], v[120:121], v[52:53]
	v_pk_mul_f32 v[22:23], v[122:123], v[40:41]
	v_pk_mul_f32 v[20:21], v[36:37], v[20:21] op_sel_hi:[0, 1]
	v_pk_mul_f32 v[22:23], v[36:37], v[22:23] op_sel_hi:[0, 1]
	s_waitcnt vmcnt(5)
	v_pk_fma_f32 v[20:21], v[124:125], v[20:21], v[116:117]
	v_pk_fma_f32 v[22:23], v[126:127], v[22:23], v[118:119]
	global_store_dwordx4 v[4:5], v[20:23], off
	s_nop 1
	s_nop 0
	s_waitcnt vmcnt(4)
	v_pk_mul_f32 v[20:21], v[132:133], v[54:55]
	v_pk_mul_f32 v[22:23], v[134:135], v[42:43]
	v_pk_mul_f32 v[20:21], v[36:37], v[20:21] op_sel_hi:[0, 1]
	v_pk_mul_f32 v[22:23], v[36:37], v[22:23] op_sel_hi:[0, 1]
	s_waitcnt vmcnt(3)
	v_pk_fma_f32 v[20:21], v[136:137], v[20:21], v[128:129]
	v_pk_fma_f32 v[22:23], v[138:139], v[22:23], v[130:131]
	global_store_dwordx4 v[4:5], v[20:23], off offset:1024
	s_nop 1
	v_lshl_add_u64 v[4:5], v[4:5], 0, s[90:91]
	s_andn2_b64 exec, exec, s[4:5]
	s_cbranch_execnz .LBB0_376
